# attention: static s_setprio 1 for waves 0-3 instead of 4-7
# speedup vs baseline: 1.0056x; 1.0056x over previous
.LBB0_1708:
	s_or_b64 exec, exec, s[0:1]
	s_and_b64 vcc, exec, s[92:93]
	s_waitcnt lgkmcnt(0)
	s_barrier
	s_cbranch_vccnz .LBB0_1794
	v_readfirstlane_b32 s32, v236
	s_nop 3
	s_cmp_lt_u32 s32, 0x100
	s_cbranch_scc0 .Lattn_prio_done
	s_setprio 1
